# phase 7 row loop: scale/shift chunk loads of rows 1-3 issued before the big wait into fresh registers (their later vmcnt ladders removed)
# speedup vs baseline: 1.0081x; 1.0081x over previous
; DI float bflo(unsigned u) { return __uint_as_float(u << 16); }
; DI float bfhi(unsigned u) { return __uint_as_float(u & 0xffff0000u); }
; DI void norm_rows_b(const Params& p) {
;     ...
;     for (int row0 = gw; row0 < NLAT; row0 += 4 * NGW) {
;         u32x4 v[4][2];
; #pragma unroll
;         for (int u = 0; u < 4; ++u)
; #pragma unroll
;             for (int j = 0; j < 2; ++j) v[u][j] = *(const u32x4*)(X1 + (size_t)(row0 + u * NGW) * DM + 8 * lane + 512 * j);
; #pragma unroll
;         for (int u = 0; u < 4; ++u) {
;             const int row = row0 + u * NGW;
;             float f[2][8]; float s = 0.f;
; #pragma unroll
;             for (int j = 0; j < 2; ++j) { const u32x4 q = v[u][j];
;                 f[j][0] = bflo(q.x); f[j][1] = bfhi(q.x); f[j][2] = bflo(q.y); f[j][3] = bfhi(q.y); f[j][4] = bflo(q.z); f[j][5] = bfhi(q.z); f[j][6] = bflo(q.w); f[j][7] = bfhi(q.w);
; #pragma unroll
;                 for (int e = 0; e < 8; ++e) s += f[j][e] * f[j][e]; }
;             const float rstd = rsqrtf(wave_sum(s) * (1.f / DM) + EPS);
;             const float* mrow = modp + (size_t)(row >> 12) * NMODC + 3072;
; #pragma unroll
;             for (int j = 0; j < 2; ++j) {
;                 const f32x4 sh0 = *(const f32x4*)(mrow + 8 * lane + 512 * j), sh1 = *(const f32x4*)(mrow + 8 * lane + 512 * j + 4);
;                 const f32x4 sc0 = *(const f32x4*)(mrow + 1024 + 8 * lane + 512 * j), sc1 = *(const f32x4*)(mrow + 1024 + 8 * lane + 512 * j + 4);
.LBB0_786:
	v_lshl_add_u64 v[20:21], v[42:43], 0, v[38:39]
	v_add_u32_e32 v22, s23, v18
	v_add_u32_e32 v24, s24, v18
	v_ashrrev_i32_e32 v19, 12, v18
	v_add_u32_e32 v28, s21, v18
	v_add_co_u32_e32 v18, vcc, 0x3437a000, v20
	v_mul_hi_i32_i24_e32 v27, 0x6000, v19
	v_mul_i32_i24_e32 v26, 0x6000, v19
	v_addc_co_u32_e32 v19, vcc, 0, v21, vcc
	v_lshl_add_u64 v[16:17], v[40:41], 0, v[38:39]
	v_add_co_u32_e64 v72, s[4:5], s38, v20
	global_load_dwordx4 v[54:57], v[18:19], off
	global_load_dwordx4 v[62:65], v[18:19], off offset:1024
	v_ashrrev_i32_e32 v23, 31, v22
	v_ashrrev_i32_e32 v25, 31, v24
	v_addc_co_u32_e64 v73, s[4:5], 0, v21, s[4:5]
	v_ashrrev_i32_e32 v29, 12, v28
	v_add_u32_e32 v85, s21, v28
	v_add_co_u32_e32 v28, vcc, s25, v16
	v_mov_b32_e32 v45, v33
	v_add_co_u32_e64 v66, s[4:5], s38, v16
	v_lshlrev_b64 v[20:21], 11, v[22:23]
	v_lshlrev_b64 v[48:49], 11, v[24:25]
	v_lshl_add_u64 v[22:23], s[30:31], 0, v[26:27]
	v_mul_hi_i32_i24_e32 v25, 0x6000, v29
	v_mul_i32_i24_e32 v24, 0x6000, v29
	v_ashrrev_i32_e32 v16, 12, v85
	v_addc_co_u32_e32 v29, vcc, 0, v17, vcc
	v_addc_co_u32_e64 v67, s[4:5], 0, v17, s[4:5]
	v_lshl_add_u64 v[26:27], v[34:35], 0, v[20:21]
	v_lshl_add_u64 v[30:31], v[34:35], 0, v[48:49]
	v_lshl_add_u64 v[50:51], v[22:23], 0, v[44:45]
	v_mul_hi_i32_i24_e32 v59, 0x6000, v16
	v_mul_i32_i24_e32 v58, 0x6000, v16
	v_lshl_add_u64 v[52:53], v[36:37], 0, v[20:21]
	global_load_dwordx4 v[68:71], v[28:29], off
	global_load_dwordx4 v[74:77], v[28:29], off offset:1024
	global_load_dwordx4 v[80:83], v[26:27], off
	global_load_dwordx4 v[20:23], v[26:27], off offset:1024
	global_load_dwordx4 v[136:139], v[30:31], off
	global_load_dwordx4 v[16:19], v[30:31], off offset:1024
	v_lshl_add_u64 v[122:123], v[50:51], 0, s[16:17]
	v_lshl_add_u64 v[124:125], v[50:51], 0, s[18:19]
	v_add_co_u32_e32 v50, vcc, s36, v50
	v_lshl_add_u64 v[24:25], s[30:31], 0, v[24:25]
	s_nop 0
	v_addc_co_u32_e32 v51, vcc, 0, v51, vcc
	v_lshl_add_u64 v[78:79], v[24:25], 0, v[44:45]
	global_load_dwordx4 v[24:27], v[50:51], off offset:-4096
	global_load_dwordx4 v[140:143], v[50:51], off
	global_load_dwordx4 v[28:31], v[122:123], off offset:16
	global_load_dwordx4 v[144:147], v[124:125], off offset:16
	v_add_co_u32_e32 v116, vcc, s36, v78
	v_lshl_add_u64 v[96:97], v[78:79], 0, s[16:17]
	v_lshl_add_u64 v[98:99], v[78:79], 0, s[18:19]
	v_addc_co_u32_e32 v117, vcc, 0, v79, vcc
	v_lshl_add_u64 v[58:59], s[30:31], 0, v[58:59]
	v_lshl_add_u64 v[50:51], v[58:59], 0, v[44:45]
	v_mov_b64_e32 v[46:47], s[22:23]
	v_add_co_u32_e32 v94, vcc, s36, v50
	v_lshl_add_u64 v[90:91], v[50:51], 0, s[16:17]
	s_nop 0
	v_addc_co_u32_e32 v95, vcc, 0, v51, vcc
	v_lshl_add_u64 v[92:93], v[50:51], 0, s[18:19]
	v_mov_b32_e32 v61, v33
	v_lshl_add_u64 v[40:41], v[40:41], 0, s[12:13]
	v_lshl_add_u64 v[42:43], v[42:43], 0, s[12:13]
	global_load_dwordx4 v[192:195], v[124:125], off offset:2048
	global_load_dwordx4 v[196:199], v[124:125], off offset:2064
	global_load_dwordx4 v[200:203], v[122:123], off offset:2048
	global_load_dwordx4 v[204:207], v[122:123], off offset:2064
	global_load_dwordx4 v[208:211], v[116:117], off
	global_load_dwordx4 v[212:215], v[98:99], off offset:16
	global_load_dwordx4 v[216:219], v[116:117], off offset:-4096
	global_load_dwordx4 v[220:223], v[96:97], off offset:16
	global_load_dwordx4 v[224:227], v[98:99], off offset:2048
	global_load_dwordx4 v[228:231], v[98:99], off offset:2064
	global_load_dwordx4 v[232:235], v[96:97], off offset:2048
	global_load_dwordx4 v[236:239], v[96:97], off offset:2064
	global_load_dwordx4 v[240:243], v[94:95], off
	global_load_dwordx4 v[244:247], v[92:93], off offset:16
	global_load_dwordx4 v[248:251], v[94:95], off offset:-4096
	global_load_dwordx4 v[252:255], v[90:91], off offset:16
	s_waitcnt vmcnt(0)
	v_and_b32_e32 v157, 0xffff0000, v54
	v_and_b32_e32 v148, 0xffff0000, v64
	v_and_b32_e32 v32, 0xffff0000, v65
	v_lshlrev_b32_e32 v111, 16, v54
	v_lshlrev_b32_e32 v151, 16, v64
	v_lshlrev_b32_e32 v153, 16, v65
	v_lshlrev_b32_e32 v115, 16, v55
	v_mov_b32_e32 v150, v148
	v_mov_b32_e32 v152, v32
	v_and_b32_e32 v155, 0xffff0000, v55
	v_lshlrev_b32_e32 v101, 16, v62
	v_and_b32_e32 v107, 0xffff0000, v62
	v_lshlrev_b32_e32 v103, 16, v63
	v_and_b32_e32 v105, 0xffff0000, v63
	v_lshlrev_b32_e32 v109, 16, v56
	v_mov_b32_e32 v166, v111
	v_mov_b32_e32 v167, v157
	v_and_b32_e32 v121, 0xffff0000, v56
	v_lshlrev_b32_e32 v113, 16, v57
	v_and_b32_e32 v119, 0xffff0000, v57
	v_mov_b32_e32 v164, v115
	v_mov_b32_e32 v165, v155
	v_mov_b32_e32 v168, v113
	v_mov_b32_e32 v169, v119
	v_and_b32_e32 v156, 0xffff0000, v68
	v_lshlrev_b32_e32 v110, 16, v68
	v_and_b32_e32 v158, 0xffff0000, v76
	v_and_b32_e32 v60, 0xffff0000, v77
	v_pk_mul_f32 v[172:173], v[156:157], v[156:157]
	v_lshlrev_b32_e32 v114, 16, v69
	v_lshlrev_b32_e32 v161, 16, v76
	v_lshlrev_b32_e32 v163, 16, v77
	v_mov_b32_e32 v160, v158
	v_mov_b32_e32 v162, v60
	v_pk_fma_f32 v[172:173], v[110:111], v[110:111], v[172:173]
	v_and_b32_e32 v154, 0xffff0000, v69
	v_lshlrev_b32_e32 v108, 16, v70
	v_and_b32_e32 v120, 0xffff0000, v70
	v_lshlrev_b32_e32 v112, 16, v71
	v_and_b32_e32 v118, 0xffff0000, v71
	v_lshlrev_b32_e32 v100, 16, v74
	v_and_b32_e32 v106, 0xffff0000, v74
	v_lshlrev_b32_e32 v102, 16, v75
	v_and_b32_e32 v104, 0xffff0000, v75
	v_lshlrev_b32_e32 v63, 16, v82
	v_and_b32_e32 v75, 0xffff0000, v81
	v_and_b32_e32 v74, 0xffff0000, v137
	v_lshlrev_b32_e32 v62, 16, v138
	v_lshlrev_b32_e32 v69, 16, v80
	v_lshlrev_b32_e32 v68, 16, v136
	v_and_b32_e32 v79, 0xffff0000, v80
	v_and_b32_e32 v78, 0xffff0000, v136
	v_lshlrev_b32_e32 v71, 16, v81
	v_lshlrev_b32_e32 v70, 16, v137
	v_and_b32_e32 v81, 0xffff0000, v82
	v_and_b32_e32 v80, 0xffff0000, v138
; DI unsigned pk2(float a, float b) { f32x2 v = {a, b}; bf16x2_t r = __builtin_convertvector(v, bf16x2_t); return __builtin_bit_cast(unsigned, r); }
; DI float bflo(unsigned u) { return __uint_as_float(u << 16); }
; DI float bfhi(unsigned u) { return __uint_as_float(u & 0xffff0000u); }
; DI void norm_rows_b(const Params& p) {
;     ...
;         for (int u = 0; u < 4; ++u) {
;             const int row = row0 + u * NGW;
;             float f[2][8]; float s = 0.f;
; #pragma unroll
;             for (int j = 0; j < 2; ++j) { const u32x4 q = v[u][j];
;                 f[j][0] = bflo(q.x); f[j][1] = bfhi(q.x); f[j][2] = bflo(q.y); f[j][3] = bfhi(q.y); f[j][4] = bflo(q.z); f[j][5] = bfhi(q.z); f[j][6] = bflo(q.w); f[j][7] = bfhi(q.w);
; #pragma unroll
;                 for (int e = 0; e < 8; ++e) s += f[j][e] * f[j][e]; }
;             const float rstd = rsqrtf(wave_sum(s) * (1.f / DM) + EPS);
;             const float* mrow = modp + (size_t)(row >> 12) * NMODC + 3072;
; #pragma unroll
;             for (int j = 0; j < 2; ++j) {
;                 const f32x4 sh0 = *(const f32x4*)(mrow + 8 * lane + 512 * j), sh1 = *(const f32x4*)(mrow + 8 * lane + 512 * j + 4);
;                 const f32x4 sc0 = *(const f32x4*)(mrow + 1024 + 8 * lane + 512 * j), sc1 = *(const f32x4*)(mrow + 1024 + 8 * lane + 512 * j + 4);
;                 const f32x4 x0 = {f[j][0], f[j][1], f[j][2], f[j][3]}, x1 = {f[j][4], f[j][5], f[j][6], f[j][7]};
;                 const f32x4 y0 = (x0 * rstd * gn[j][0]) * (sc0 + 1.f) + sh0, y1 = (x1 * rstd * gn[j][1]) * (sc1 + 1.f) + sh1;
;                 u32x4 o; o.x = pk2(y0.x, y0.y); o.y = pk2(y0.z, y0.w); o.z = pk2(y1.x, y1.y); o.w = pk2(y1.z, y1.w);
;                 *(u32x4*)(H2 + (size_t)row * DM + 8 * lane + 512 * j) = o;
;             }
	v_lshlrev_b32_e32 v76, 16, v139
	v_and_b32_e32 v82, 0xffff0000, v139
	v_pk_mul_f32 v[136:137], v[150:151], v[150:151]
	v_pk_mul_f32 v[138:139], v[152:153], v[152:153]
	v_pk_mul_f32 v[184:185], v[160:161], v[160:161]
	v_pk_mul_f32 v[186:187], v[162:163], v[162:163]
	v_pk_fma_f32 v[172:173], v[114:115], v[114:115], v[172:173]
	v_mov_b32_e32 v157, v137
	v_mov_b32_e32 v137, v139
	v_mov_b32_e32 v111, v156
	v_mov_b32_e32 v156, v185
	v_mov_b32_e32 v185, v136
	v_mov_b32_e32 v136, v187
	v_mov_b32_e32 v187, v138
	v_pk_fma_f32 v[138:139], v[154:155], v[154:155], v[172:173]
	v_mov_b32_e32 v115, v154
	v_pk_fma_f32 v[138:139], v[108:109], v[108:109], v[138:139]
	v_lshlrev_b32_e32 v55, 16, v20
	v_pk_fma_f32 v[138:139], v[120:121], v[120:121], v[138:139]
	v_and_b32_e32 v57, 0xffff0000, v20
	v_pk_fma_f32 v[138:139], v[112:113], v[112:113], v[138:139]
	v_lshlrev_b32_e32 v58, 16, v17
	v_pk_fma_f32 v[138:139], v[118:119], v[118:119], v[138:139]
	v_and_b32_e32 v20, 0xffff0000, v17
	v_pk_fma_f32 v[138:139], v[100:101], v[100:101], v[138:139]
	v_and_b32_e32 v84, 0xffff0000, v22
	v_pk_fma_f32 v[138:139], v[106:107], v[106:107], v[138:139]
	v_lshlrev_b32_e32 v89, 16, v22
	v_pk_fma_f32 v[138:139], v[102:103], v[102:103], v[138:139]
	v_and_b32_e32 v22, 0xffff0000, v18
	v_pk_fma_f32 v[138:139], v[104:105], v[104:105], v[138:139]
	v_lshlrev_b32_e32 v51, 16, v18
	v_pk_add_f32 v[138:139], v[156:157], v[138:139]
	v_mov_b32_e32 v170, v109
	v_pk_add_f32 v[138:139], v[184:185], v[138:139]
	v_mov_b32_e32 v171, v121
	v_pk_add_f32 v[136:137], v[136:137], v[138:139]
	v_pk_add_f32 v[142:143], v[142:143], 1.0 op_sel_hi:[1,0]
	v_pk_add_f32 v[136:137], v[186:187], v[136:137]
	s_nop 1
	v_mov_b32_dpp v139, v137 quad_perm:[1,0,3,2] row_mask:0xf bank_mask:0xf
	s_nop 1
	v_mov_b32_dpp v138, v136 quad_perm:[1,0,3,2] row_mask:0xf bank_mask:0xf
	v_pk_add_f32 v[140:141], v[140:141], 1.0 op_sel_hi:[1,0]
	v_pk_add_f32 v[146:147], v[146:147], 1.0 op_sel_hi:[1,0]
	v_pk_add_f32 v[144:145], v[144:145], 1.0 op_sel_hi:[1,0]
	v_and_b32_e32 v149, s0, v65
	s_waitcnt lgkmcnt(0)
	v_pk_add_f32 v[136:137], v[136:137], v[138:139]
	s_nop 1
	v_mov_b32_dpp v139, v137 quad_perm:[2,3,0,1] row_mask:0xf bank_mask:0xf
	s_nop 1
	v_mov_b32_dpp v138, v136 quad_perm:[2,3,0,1] row_mask:0xf bank_mask:0xf
	v_pk_mov_b32 v[148:149], v[150:151], v[148:149] op_sel:[1,0]
	v_pk_mul_f32 v[150:151], v[78:79], v[78:79]
	v_mov_b32_e32 v126, v103
	v_mov_b32_e32 v127, v105
	s_waitcnt lgkmcnt(0)
	v_pk_add_f32 v[136:137], v[136:137], v[138:139]
	s_nop 1
	v_mov_b32_dpp v139, v137 row_half_mirror row_mask:0xf bank_mask:0xf
	s_nop 1
	v_mov_b32_dpp v138, v136 row_half_mirror row_mask:0xf bank_mask:0xf
	v_mov_b32_e32 v128, v101
	v_mov_b32_e32 v129, v107
	v_pk_mov_b32 v[152:153], v[152:153], v[32:33] op_sel:[1,0]
	v_pk_fma_f32 v[150:151], v[68:69], v[68:69], v[150:151]
	s_waitcnt lgkmcnt(0)
	v_pk_add_f32 v[136:137], v[136:137], v[138:139]
	s_nop 1
	v_mov_b32_dpp v139, v137 row_ror:8 row_mask:0xf bank_mask:0xf
	s_nop 1
	v_mov_b32_dpp v138, v136 row_ror:8 row_mask:0xf bank_mask:0xf
	v_mov_b32_e32 v109, v120
	v_mov_b32_e32 v113, v118
	v_and_b32_e32 v159, s0, v77
	v_pk_mov_b32 v[60:61], v[162:163], v[60:61] op_sel:[1,0]
	s_waitcnt lgkmcnt(0)
	v_pk_add_f32 v[136:137], v[136:137], v[138:139]
	ds_bpermute_b32 v139, v134, v137
	ds_bpermute_b32 v138, v134, v136
	v_pk_mov_b32 v[158:159], v[160:161], v[158:159] op_sel:[1,0]
	v_mov_b32_e32 v101, v106
	v_mov_b32_e32 v103, v104
	v_lshlrev_b32_e32 v77, 16, v83
	s_waitcnt lgkmcnt(0)
	v_pk_add_f32 v[136:137], v[136:137], v[138:139]
	ds_bpermute_b32 v139, v135, v137
	ds_bpermute_b32 v138, v135, v136
	v_and_b32_e32 v83, 0xffff0000, v83
	v_lshlrev_b32_e32 v54, 16, v16
	v_and_b32_e32 v56, 0xffff0000, v16
	v_lshlrev_b32_e32 v59, 16, v21
	s_waitcnt lgkmcnt(0)
	v_pk_add_f32 v[136:137], v[136:137], v[138:139]
	v_mov_b32_e32 v88, v84
	v_pk_fma_f32 v[154:155], v[136:137], s[20:21], v[46:47] op_sel_hi:[1,0,0]
	v_mov_b32_e32 v50, v22
	v_mul_f32_e32 v17, 0x4b800000, v155
	v_cmp_gt_f32_e32 vcc, s37, v155
	v_and_b32_e32 v21, 0xffff0000, v21
	v_and_b32_e32 v16, 0xffff0000, v19
	v_cndmask_b32_e32 v17, v155, v17, vcc
	v_rsq_f32_e32 v17, v17
	v_and_b32_e32 v32, 0xffff0000, v23
	v_pk_mul_f32 v[160:161], v[88:89], v[88:89]
	v_pk_mul_f32 v[162:163], v[50:51], v[50:51]
	v_mul_f32_e32 v18, 0x45800000, v17
	v_cndmask_b32_e32 v18, v17, v18, vcc
	v_pk_mul_f32 v[136:137], v[164:165], v[18:19] op_sel_hi:[1,0]
	v_pk_mul_f32 v[138:139], v[166:167], v[18:19] op_sel_hi:[1,0]
	v_pk_mul_f32 v[156:157], v[168:169], v[18:19] op_sel_hi:[1,0]
	v_pk_mul_f32 v[164:165], v[170:171], v[18:19] op_sel_hi:[1,0]
	v_pk_mul_f32 v[138:139], v[4:5], v[138:139]
	v_pk_mul_f32 v[136:137], v[6:7], v[136:137]
	v_pk_mul_f32 v[164:165], v[0:1], v[164:165]
	v_pk_mul_f32 v[156:157], v[2:3], v[156:157]
	v_pk_fma_f32 v[26:27], v[142:143], v[136:137], v[26:27]
	v_pk_fma_f32 v[24:25], v[140:141], v[138:139], v[24:25]
	v_pk_fma_f32 v[30:31], v[146:147], v[156:157], v[30:31]
	v_pk_fma_f32 v[28:29], v[144:145], v[164:165], v[28:29]
	v_cvt_pk_bf16_f32 v24, v24, v25
	v_cvt_pk_bf16_f32 v25, v26, v27
	v_cvt_pk_bf16_f32 v26, v28, v29
	v_cvt_pk_bf16_f32 v27, v30, v31
	global_store_dwordx4 v[72:73], v[24:27], off
	v_pk_fma_f32 v[142:143], v[70:71], v[70:71], v[150:151]
	v_pk_mul_f32 v[126:127], v[126:127], v[18:19] op_sel_hi:[1,0]
	v_pk_mul_f32 v[128:129], v[128:129], v[18:19] op_sel_hi:[1,0]
	v_pk_mul_f32 v[150:151], v[18:19], v[152:153] op_sel_hi:[0,1]
	v_pk_mul_f32 v[148:149], v[18:19], v[148:149] op_sel_hi:[0,1]
	v_pk_mul_f32 v[128:129], v[12:13], v[128:129]
	v_pk_mul_f32 v[126:127], v[14:15], v[126:127]
	v_pk_mul_f32 v[148:149], v[8:9], v[148:149]
; DI unsigned pk2(float a, float b) { f32x2 v = {a, b}; bf16x2_t r = __builtin_convertvector(v, bf16x2_t); return __builtin_bit_cast(unsigned, r); }
; DI void norm_rows_b(const Params& p) {
;     ...
; #pragma unroll
;             for (int j = 0; j < 2; ++j) {
;                 const f32x4 sh0 = *(const f32x4*)(mrow + 8 * lane + 512 * j), sh1 = *(const f32x4*)(mrow + 8 * lane + 512 * j + 4);
;                 const f32x4 sc0 = *(const f32x4*)(mrow + 1024 + 8 * lane + 512 * j), sc1 = *(const f32x4*)(mrow + 1024 + 8 * lane + 512 * j + 4);
;                 const f32x4 x0 = {f[j][0], f[j][1], f[j][2], f[j][3]}, x1 = {f[j][4], f[j][5], f[j][6], f[j][7]};
;                 const f32x4 y0 = (x0 * rstd * gn[j][0]) * (sc0 + 1.f) + sh0, y1 = (x1 * rstd * gn[j][1]) * (sc1 + 1.f) + sh1;
;                 u32x4 o; o.x = pk2(y0.x, y0.y); o.y = pk2(y0.z, y0.w); o.z = pk2(y1.x, y1.y); o.w = pk2(y1.z, y1.w);
;                 *(u32x4*)(H2 + (size_t)row * DM + 8 * lane + 512 * j) = o;
;             }
	v_pk_mul_f32 v[150:151], v[10:11], v[150:151]
	v_mul_f32_e32 v17, 0x4b800000, v154
	v_cmp_gt_f32_e32 vcc, s37, v154
	v_pk_fma_f32 v[142:143], v[74:75], v[74:75], v[142:143]
	v_lshlrev_b32_e32 v87, 16, v23
	v_cndmask_b32_e32 v17, v154, v17, vcc
	v_rsq_f32_e32 v17, v17
	v_lshlrev_b32_e32 v65, 16, v19
	v_mov_b32_e32 v64, v16
	v_mov_b32_e32 v86, v32
	v_mul_f32_e32 v18, 0x45800000, v17
	v_cndmask_b32_e32 v18, v17, v18, vcc
	v_pk_mul_f32 v[114:115], v[114:115], v[18:19] op_sel_hi:[1,0]
	v_pk_mul_f32 v[110:111], v[110:111], v[18:19] op_sel_hi:[1,0]
	v_pk_mul_f32 v[112:113], v[112:113], v[18:19] op_sel_hi:[1,0]
	v_pk_mul_f32 v[108:109], v[108:109], v[18:19] op_sel_hi:[1,0]
	v_pk_mul_f32 v[110:111], v[4:5], v[110:111]
	v_pk_mul_f32 v[114:115], v[6:7], v[114:115]
	v_pk_mul_f32 v[108:109], v[0:1], v[108:109]
	v_pk_mul_f32 v[112:113], v[2:3], v[112:113]
	v_pk_mul_f32 v[102:103], v[102:103], v[18:19] op_sel_hi:[1,0]
	v_pk_mul_f32 v[100:101], v[100:101], v[18:19] op_sel_hi:[1,0]
	v_pk_mul_f32 v[60:61], v[18:19], v[60:61] op_sel_hi:[0,1]
	v_pk_mul_f32 v[106:107], v[18:19], v[158:159] op_sel_hi:[0,1]
	v_pk_mul_f32 v[100:101], v[12:13], v[100:101]
	v_pk_mul_f32 v[102:103], v[14:15], v[102:103]
	v_pk_mul_f32 v[106:107], v[8:9], v[106:107]
	v_pk_mul_f32 v[60:61], v[10:11], v[60:61]
	v_mov_b32_e32 v144, v163
	v_mov_b32_e32 v145, v161
	v_pk_mul_f32 v[188:189], v[64:65], v[64:65]
	v_pk_mul_f32 v[140:141], v[86:87], v[86:87]
	v_mov_b32_e32 v163, v160
	v_mov_b32_e32 v146, v189
	v_mov_b32_e32 v147, v141
	v_mov_b32_e32 v189, v140
	v_mov_b32_e32 v174, v71
	v_mov_b32_e32 v175, v75
	v_mov_b32_e32 v176, v69
	v_mov_b32_e32 v177, v79
	v_mov_b32_e32 v178, v77
	v_mov_b32_e32 v179, v83
	v_mov_b32_e32 v182, v63
	v_mov_b32_e32 v183, v81
	v_add_u32_e32 v75, s21, v85
	v_and_b32_e32 v85, s0, v23
	v_pk_mov_b32 v[84:85], v[88:89], v[84:85] op_sel:[1,0]
	v_pk_mov_b32 v[86:87], v[86:87], v[32:33] op_sel:[1,0]
	v_mov_b32_e32 v69, v78
	v_mov_b32_e32 v71, v74
	v_and_b32_e32 v23, s0, v19
	v_pk_mov_b32 v[22:23], v[50:51], v[22:23] op_sel:[1,0]
	v_pk_add_f32 v[194:195], v[194:195], 1.0 op_sel_hi:[1,0]
	v_pk_add_f32 v[192:193], v[192:193], 1.0 op_sel_hi:[1,0]
	v_pk_add_f32 v[198:199], v[198:199], 1.0 op_sel_hi:[1,0]
	v_pk_add_f32 v[196:197], v[196:197], 1.0 op_sel_hi:[1,0]
	v_pk_fma_f32 v[194:195], v[194:195], v[126:127], v[202:203]
	v_pk_fma_f32 v[192:193], v[192:193], v[128:129], v[200:201]
	v_pk_fma_f32 v[198:199], v[198:199], v[150:151], v[206:207]
	v_pk_fma_f32 v[196:197], v[196:197], v[148:149], v[204:205]
	v_cvt_pk_bf16_f32 v192, v192, v193
	v_cvt_pk_bf16_f32 v193, v194, v195
	v_cvt_pk_bf16_f32 v194, v196, v197
	v_cvt_pk_bf16_f32 v195, v198, v199
	global_store_dwordx4 v[72:73], v[192:195], off offset:1024
	v_pk_fma_f32 v[72:73], v[62:63], v[62:63], v[142:143]
	v_mov_b32_e32 v63, v80
	v_pk_fma_f32 v[72:73], v[80:81], v[80:81], v[72:73]
	v_pk_add_f32 v[210:211], v[210:211], 1.0 op_sel_hi:[1,0]
	v_pk_add_f32 v[208:209], v[208:209], 1.0 op_sel_hi:[1,0]
	v_pk_add_f32 v[214:215], v[214:215], 1.0 op_sel_hi:[1,0]
	v_pk_add_f32 v[212:213], v[212:213], 1.0 op_sel_hi:[1,0]
	v_pk_fma_f32 v[210:211], v[210:211], v[114:115], v[218:219]
	v_pk_fma_f32 v[208:209], v[208:209], v[110:111], v[216:217]
	v_pk_fma_f32 v[214:215], v[214:215], v[112:113], v[222:223]
	v_pk_fma_f32 v[212:213], v[212:213], v[108:109], v[220:221]
	v_cvt_pk_bf16_f32 v208, v208, v209
	v_cvt_pk_bf16_f32 v209, v210, v211
	v_cvt_pk_bf16_f32 v210, v212, v213
	v_cvt_pk_bf16_f32 v211, v214, v215
	global_store_dwordx4 v[66:67], v[208:211], off
	v_pk_fma_f32 v[72:73], v[76:77], v[76:77], v[72:73]
	v_mov_b32_e32 v77, v82
	v_pk_fma_f32 v[72:73], v[82:83], v[82:83], v[72:73]
	v_pk_add_f32 v[226:227], v[226:227], 1.0 op_sel_hi:[1,0]
	v_pk_add_f32 v[224:225], v[224:225], 1.0 op_sel_hi:[1,0]
	v_pk_add_f32 v[230:231], v[230:231], 1.0 op_sel_hi:[1,0]
	v_pk_add_f32 v[228:229], v[228:229], 1.0 op_sel_hi:[1,0]
	v_pk_fma_f32 v[226:227], v[226:227], v[102:103], v[234:235]
	v_pk_fma_f32 v[224:225], v[224:225], v[100:101], v[232:233]
	v_pk_fma_f32 v[230:231], v[230:231], v[60:61], v[238:239]
	v_pk_fma_f32 v[228:229], v[228:229], v[106:107], v[236:237]
	v_cvt_pk_bf16_f32 v224, v224, v225
	v_cvt_pk_bf16_f32 v225, v226, v227
	v_cvt_pk_bf16_f32 v226, v228, v229
	v_cvt_pk_bf16_f32 v227, v230, v231
	global_store_dwordx4 v[66:67], v[224:227], off offset:1024
	v_pk_fma_f32 v[72:73], v[54:55], v[54:55], v[72:73]
	v_pk_add_f32 v[242:243], v[242:243], 1.0 op_sel_hi:[1,0]
	v_pk_fma_f32 v[72:73], v[56:57], v[56:57], v[72:73]
	v_pk_add_f32 v[240:241], v[240:241], 1.0 op_sel_hi:[1,0]
	v_pk_fma_f32 v[72:73], v[58:59], v[58:59], v[72:73]
	v_pk_add_f32 v[246:247], v[246:247], 1.0 op_sel_hi:[1,0]
	v_pk_fma_f32 v[72:73], v[20:21], v[20:21], v[72:73]
	v_pk_add_f32 v[244:245], v[244:245], 1.0 op_sel_hi:[1,0]
	v_pk_add_f32 v[72:73], v[144:145], v[72:73]
	s_nop 0
	v_pk_add_f32 v[72:73], v[162:163], v[72:73]
	s_nop 0
	v_pk_add_f32 v[72:73], v[146:147], v[72:73]
	s_nop 0
	v_pk_add_f32 v[72:73], v[188:189], v[72:73]
	s_nop 1
	v_mov_b32_dpp v105, v73 quad_perm:[1,0,3,2] row_mask:0xf bank_mask:0xf
	s_nop 1
	v_mov_b32_dpp v104, v72 quad_perm:[1,0,3,2] row_mask:0xf bank_mask:0xf
	s_waitcnt lgkmcnt(0)
	v_pk_add_f32 v[72:73], v[72:73], v[104:105]
	s_nop 1
	v_mov_b32_dpp v105, v73 quad_perm:[2,3,0,1] row_mask:0xf bank_mask:0xf
	s_nop 1
	v_mov_b32_dpp v104, v72 quad_perm:[2,3,0,1] row_mask:0xf bank_mask:0xf
	s_waitcnt lgkmcnt(0)
	v_pk_add_f32 v[72:73], v[72:73], v[104:105]
	s_nop 1
	v_mov_b32_dpp v105, v73 row_half_mirror row_mask:0xf bank_mask:0xf
	s_nop 1
	v_mov_b32_dpp v104, v72 row_half_mirror row_mask:0xf bank_mask:0xf
	s_waitcnt lgkmcnt(0)
; DI unsigned pk2(float a, float b) { f32x2 v = {a, b}; bf16x2_t r = __builtin_convertvector(v, bf16x2_t); return __builtin_bit_cast(unsigned, r); }
; DI void norm_rows_b(const Params& p) {
;     ...
; #pragma unroll
;             for (int j = 0; j < 2; ++j) {
;                 const f32x4 sh0 = *(const f32x4*)(mrow + 8 * lane + 512 * j), sh1 = *(const f32x4*)(mrow + 8 * lane + 512 * j + 4);
;                 const f32x4 sc0 = *(const f32x4*)(mrow + 1024 + 8 * lane + 512 * j), sc1 = *(const f32x4*)(mrow + 1024 + 8 * lane + 512 * j + 4);
;                 const f32x4 x0 = {f[j][0], f[j][1], f[j][2], f[j][3]}, x1 = {f[j][4], f[j][5], f[j][6], f[j][7]};
;                 const f32x4 y0 = (x0 * rstd * gn[j][0]) * (sc0 + 1.f) + sh0, y1 = (x1 * rstd * gn[j][1]) * (sc1 + 1.f) + sh1;
;                 u32x4 o; o.x = pk2(y0.x, y0.y); o.y = pk2(y0.z, y0.w); o.z = pk2(y1.x, y1.y); o.w = pk2(y1.z, y1.w);
;                 *(u32x4*)(H2 + (size_t)row * DM + 8 * lane + 512 * j) = o;
;             }
	v_pk_add_f32 v[60:61], v[72:73], v[104:105]
	s_nop 1
	v_mov_b32_dpp v67, v61 row_ror:8 row_mask:0xf bank_mask:0xf
	s_nop 1
	v_mov_b32_dpp v66, v60 row_ror:8 row_mask:0xf bank_mask:0xf
	s_waitcnt lgkmcnt(0)
	v_pk_add_f32 v[60:61], v[60:61], v[66:67]
	ds_bpermute_b32 v67, v134, v61
	ds_bpermute_b32 v66, v134, v60
	s_waitcnt lgkmcnt(0)
	v_pk_add_f32 v[60:61], v[60:61], v[66:67]
	ds_bpermute_b32 v67, v135, v61
	ds_bpermute_b32 v66, v135, v60
	s_waitcnt lgkmcnt(0)
	v_pk_add_f32 v[60:61], v[60:61], v[66:67]
	s_nop 0
	v_pk_fma_f32 v[46:47], v[60:61], s[20:21], v[46:47] op_sel_hi:[1,0,0]
	s_nop 0
	v_mul_f32_e32 v17, 0x4b800000, v47
	v_cmp_gt_f32_e32 vcc, s37, v47
	s_nop 1
	v_cndmask_b32_e32 v17, v47, v17, vcc
	v_rsq_f32_e32 v17, v17
	s_nop 0
	v_mul_f32_e32 v18, 0x45800000, v17
	v_cndmask_b32_e32 v18, v17, v18, vcc
	v_pk_mul_f32 v[60:61], v[174:175], v[18:19] op_sel_hi:[1,0]
	v_pk_mul_f32 v[66:67], v[176:177], v[18:19] op_sel_hi:[1,0]
	v_pk_mul_f32 v[72:73], v[178:179], v[18:19] op_sel_hi:[1,0]
	v_pk_mul_f32 v[94:95], v[182:183], v[18:19] op_sel_hi:[1,0]
	v_pk_mul_f32 v[66:67], v[4:5], v[66:67]
	v_pk_mul_f32 v[60:61], v[6:7], v[60:61]
	v_pk_mul_f32 v[94:95], v[0:1], v[94:95]
	v_pk_mul_f32 v[72:73], v[2:3], v[72:73]
	v_pk_fma_f32 v[242:243], v[242:243], v[60:61], v[250:251]
	v_pk_fma_f32 v[240:241], v[240:241], v[66:67], v[248:249]
	v_pk_fma_f32 v[246:247], v[246:247], v[72:73], v[254:255]
	v_pk_fma_f32 v[244:245], v[244:245], v[94:95], v[252:253]
	v_cvt_pk_bf16_f32 v240, v240, v241
	v_cvt_pk_bf16_f32 v241, v242, v243
	v_cvt_pk_bf16_f32 v242, v244, v245
	v_cvt_pk_bf16_f32 v243, v246, v247
	global_store_dwordx4 v[52:53], v[240:243], off
	global_load_dwordx4 v[24:27], v[92:93], off offset:2048
	s_nop 0
	global_load_dwordx4 v[28:31], v[92:93], off offset:2064
	global_load_dwordx4 v[94:97], v[90:91], off offset:2048
	global_load_dwordx4 v[98:101], v[90:91], off offset:2064
	v_ashrrev_i32_e32 v17, 12, v75
	v_mov_b32_e32 v90, v59
	v_mov_b32_e32 v91, v21
	v_mov_b32_e32 v92, v55
	v_mov_b32_e32 v93, v57
	v_mul_hi_i32_i24_e32 v61, 0x6000, v17
	v_mul_i32_i24_e32 v60, 0x6000, v17
	v_pk_mul_f32 v[88:89], v[90:91], v[18:19] op_sel_hi:[1,0]
	v_pk_mul_f32 v[90:91], v[92:93], v[18:19] op_sel_hi:[1,0]
	v_pk_mul_f32 v[86:87], v[18:19], v[86:87] op_sel_hi:[0,1]
	v_pk_mul_f32 v[84:85], v[18:19], v[84:85] op_sel_hi:[0,1]
	v_lshl_add_u64 v[60:61], s[30:31], 0, v[60:61]
	v_pk_mul_f32 v[90:91], v[12:13], v[90:91]
	v_pk_mul_f32 v[88:89], v[14:15], v[88:89]
	v_pk_mul_f32 v[84:85], v[8:9], v[84:85]
	v_pk_mul_f32 v[86:87], v[10:11], v[86:87]
	v_lshl_add_u64 v[60:61], v[60:61], 0, v[44:45]
	v_lshl_add_u64 v[66:67], v[60:61], 0, s[16:17]
	v_lshl_add_u64 v[72:73], v[60:61], 0, s[18:19]
	v_add_co_u32_e32 v60, vcc, s36, v60
	v_mul_f32_e32 v17, 0x4b800000, v46
	s_nop 0
	v_addc_co_u32_e32 v61, vcc, 0, v61, vcc
	v_cmp_gt_f32_e32 vcc, s37, v46
	v_mov_b32_e32 v55, v56
	v_mov_b32_e32 v59, v20
	v_cndmask_b32_e32 v17, v46, v17, vcc
	v_rsq_f32_e32 v17, v17
	s_waitcnt vmcnt(3)
	v_pk_add_f32 v[26:27], v[26:27], 1.0 op_sel_hi:[1,0]
	v_pk_add_f32 v[24:25], v[24:25], 1.0 op_sel_hi:[1,0]
	s_waitcnt vmcnt(2)
	v_pk_add_f32 v[30:31], v[30:31], 1.0 op_sel_hi:[1,0]
	v_pk_add_f32 v[28:29], v[28:29], 1.0 op_sel_hi:[1,0]
	s_waitcnt vmcnt(1)
	v_pk_fma_f32 v[26:27], v[26:27], v[88:89], v[96:97]
	v_pk_fma_f32 v[24:25], v[24:25], v[90:91], v[94:95]
	s_waitcnt vmcnt(0)
	v_pk_fma_f32 v[30:31], v[30:31], v[86:87], v[100:101]
	v_pk_fma_f32 v[28:29], v[28:29], v[84:85], v[98:99]
	v_cvt_pk_bf16_f32 v24, v24, v25
	v_cvt_pk_bf16_f32 v25, v26, v27
	v_cvt_pk_bf16_f32 v26, v28, v29
	v_cvt_pk_bf16_f32 v27, v30, v31
	global_store_dwordx4 v[52:53], v[24:27], off offset:1024
	global_load_dwordx4 v[24:27], v[60:61], off
	s_nop 0
	global_load_dwordx4 v[28:31], v[72:73], off offset:16
	global_load_dwordx4 v[84:87], v[60:61], off offset:-4096
	global_load_dwordx4 v[88:91], v[66:67], off offset:16
	v_mul_f32_e32 v18, 0x45800000, v17
	v_cndmask_b32_e32 v32, v17, v18, vcc
	v_lshl_add_u64 v[52:53], v[36:37], 0, v[48:49]
	v_pk_mul_f32 v[46:47], v[70:71], v[32:33] op_sel_hi:[1,0]
	v_pk_mul_f32 v[48:49], v[68:69], v[32:33] op_sel_hi:[1,0]
	v_pk_mul_f32 v[60:61], v[76:77], v[32:33] op_sel_hi:[1,0]
	v_pk_mul_f32 v[62:63], v[62:63], v[32:33] op_sel_hi:[1,0]
	v_pk_mul_f32 v[48:49], v[4:5], v[48:49]
	v_pk_mul_f32 v[46:47], v[6:7], v[46:47]
	v_pk_mul_f32 v[62:63], v[0:1], v[62:63]
	v_pk_mul_f32 v[60:61], v[2:3], v[60:61]
	v_mov_b32_e32 v17, v33
	v_pk_mov_b32 v[16:17], v[64:65], v[16:17] op_sel:[1,0]
	v_pk_mul_f32 v[20:21], v[58:59], v[32:33] op_sel_hi:[1,0]
	v_pk_mul_f32 v[50:51], v[54:55], v[32:33] op_sel_hi:[1,0]
	v_pk_mul_f32 v[16:17], v[32:33], v[16:17] op_sel_hi:[0,1]
	v_pk_mul_f32 v[22:23], v[32:33], v[22:23] op_sel_hi:[0,1]
	v_add_u32_e32 v18, s21, v75
	v_pk_mul_f32 v[50:51], v[12:13], v[50:51]
	v_pk_mul_f32 v[20:21], v[14:15], v[20:21]
	v_pk_mul_f32 v[22:23], v[8:9], v[22:23]
	v_pk_mul_f32 v[16:17], v[10:11], v[16:17]
	v_cmp_lt_i32_e32 vcc, s39, v18
	s_or_b64 s[14:15], vcc, s[14:15]
	s_waitcnt vmcnt(3)
	v_pk_add_f32 v[26:27], v[26:27], 1.0 op_sel_hi:[1,0]
	v_pk_add_f32 v[24:25], v[24:25], 1.0 op_sel_hi:[1,0]
	s_waitcnt vmcnt(2)
	v_pk_add_f32 v[30:31], v[30:31], 1.0 op_sel_hi:[1,0]
	v_pk_add_f32 v[28:29], v[28:29], 1.0 op_sel_hi:[1,0]
	s_waitcnt vmcnt(1)
	v_pk_fma_f32 v[26:27], v[26:27], v[46:47], v[86:87]
	v_pk_fma_f32 v[24:25], v[24:25], v[48:49], v[84:85]
	s_waitcnt vmcnt(0)
	v_pk_fma_f32 v[30:31], v[30:31], v[60:61], v[90:91]
	v_pk_fma_f32 v[28:29], v[28:29], v[62:63], v[88:89]
	v_cvt_pk_bf16_f32 v24, v24, v25
	v_cvt_pk_bf16_f32 v25, v26, v27
	v_cvt_pk_bf16_f32 v26, v28, v29
	v_cvt_pk_bf16_f32 v27, v30, v31
	global_store_dwordx4 v[52:53], v[24:27], off
	global_load_dwordx4 v[24:27], v[72:73], off offset:2048
	s_nop 0
	global_load_dwordx4 v[28:31], v[72:73], off offset:2064
	global_load_dwordx4 v[46:49], v[66:67], off offset:2048
	global_load_dwordx4 v[60:63], v[66:67], off offset:2064
	s_waitcnt vmcnt(3)
	v_pk_add_f32 v[26:27], v[26:27], 1.0 op_sel_hi:[1,0]
	v_pk_add_f32 v[24:25], v[24:25], 1.0 op_sel_hi:[1,0]
	s_waitcnt vmcnt(2)
	v_pk_add_f32 v[30:31], v[30:31], 1.0 op_sel_hi:[1,0]
	v_pk_add_f32 v[28:29], v[28:29], 1.0 op_sel_hi:[1,0]
	s_waitcnt vmcnt(1)
	v_pk_fma_f32 v[26:27], v[26:27], v[20:21], v[48:49]
	v_pk_fma_f32 v[20:21], v[24:25], v[50:51], v[46:47]
	s_waitcnt vmcnt(0)
	v_pk_fma_f32 v[16:17], v[30:31], v[16:17], v[62:63]
	v_pk_fma_f32 v[22:23], v[28:29], v[22:23], v[60:61]
	v_cvt_pk_bf16_f32 v20, v20, v21
	v_cvt_pk_bf16_f32 v21, v26, v27
	v_cvt_pk_bf16_f32 v22, v22, v23
	v_cvt_pk_bf16_f32 v23, v16, v17
	global_store_dwordx4 v[52:53], v[20:23], off offset:1024
	s_andn2_b64 exec, exec, s[14:15]
	s_cbranch_execnz .LBB0_786
